# deferred prep on second block with the working block at raised wave priority during the recurrent phase; conv row prefetch
# baseline (speedup 1.0000x reference)
.LBB0_299:
	s_cmp_lt_i32 s8, 3
	s_cselect_b64 s[0:1], -1, 0
	s_cmp_gt_i32 s9, 2
	s_cselect_b64 s[2:3], -1, 0
	s_and_b64 s[0:1], s[0:1], s[2:3]
	s_andn2_b64 vcc, exec, s[0:1]
	s_cbranch_vccnz .LBB0_520
	s_cmp_lg_u32 s99, 0x7fffffff
	s_cbranch_scc0 .Lprep2_go
	s_setprio 3
	s_branch .Lprep2_skip
.Lprep2_go:
	s_add_i32 s2, s100, 0x2c0
	s_mov_b32 s39, 0
	s_cmpk_lt_i32 s2, 0x1120
	s_cselect_b64 s[4:5], -1, 0
	s_and_b64 s[0:1], s[4:5], exec
	s_cselect_b32 s0, s2, 0
	s_add_u32 s3, s90, 0x19a88000
	s_addc_u32 s33, s91, 0
	s_add_u32 s8, s90, 0x1bbc8000
	s_addc_u32 s9, s91, 0
	s_add_u32 s10, s90, 0x1b3c8000
	s_addc_u32 s11, s91, 0
	s_add_u32 s12, s90, 0x1ab88000
	s_addc_u32 s13, s91, 0
	s_add_u32 s14, s90, 0x1b108000
	s_addc_u32 s15, s91, 0
	v_readlane_b32 s16, v254, 13
	s_cmpk_lt_i32 s0, 0x2c0
	v_readlane_b32 s28, v254, 25
	v_readlane_b32 s29, v254, 26
	v_readlane_b32 s30, v254, 27
	v_readlane_b32 s31, v254, 28
	v_readlane_b32 s17, v254, 14
	v_readlane_b32 s18, v254, 15
	v_readlane_b32 s19, v254, 16
	v_readlane_b32 s20, v254, 17
	v_readlane_b32 s21, v254, 18
	v_readlane_b32 s22, v254, 19
	v_readlane_b32 s23, v254, 20
	v_readlane_b32 s24, v254, 21
	v_readlane_b32 s25, v254, 22
	v_readlane_b32 s26, v254, 23
	v_readlane_b32 s27, v254, 24
	s_cbranch_scc1 .Lq_10
	s_cmpk_lt_u32 s0, 0x420
	s_cbranch_scc1 .Lq_11
	v_mov_b32_e32 v2, 0x620
	v_sub_co_u32_e32 v2, vcc, s0, v2
	v_readlane_b32 s72, v254, 29
	v_readfirstlane_b32 s16, v2
	s_and_b32 s40, s0, 31
	s_and_b64 vcc, exec, vcc
	v_readlane_b32 s73, v254, 30
	v_readlane_b32 s74, v254, 31
	v_readlane_b32 s75, v254, 32
	v_readlane_b32 s78, v254, 35
	v_readlane_b32 s79, v254, 36
	v_readlane_b32 s80, v254, 37
	v_readlane_b32 s81, v254, 38
	v_readlane_b32 s76, v254, 33
	v_readlane_b32 s77, v254, 34
	v_readlane_b32 s82, v254, 39
	v_readlane_b32 s83, v254, 40
	v_readlane_b32 s84, v254, 41
	v_readlane_b32 s85, v254, 42
	v_readlane_b32 s86, v254, 43
	v_readlane_b32 s87, v254, 44
	s_cbranch_vccnz .Lq_12
	v_mov_b32_e32 v2, 0x820
	v_sub_co_u32_e32 v2, vcc, s0, v2
	s_nop 0
	v_readfirstlane_b32 s1, v2
	s_and_b64 vcc, exec, vcc
	s_cbranch_vccnz .Lq_13
	v_mov_b32_e32 v2, 0x920
	v_readlane_b32 s16, v254, 0
	v_sub_co_u32_e32 v7, vcc, s0, v2
	s_nop 0
	v_readfirstlane_b32 s16, v7
	v_readlane_b32 s17, v254, 1
	s_lshr_b32 s16, s16, 5
	v_readlane_b32 s18, v254, 2
	s_mul_hi_u32 s17, s16, 0x44000
	s_mul_i32 s16, s16, 0x44000
	v_readlane_b32 s19, v254, 3
	v_readlane_b32 s20, v254, 4
	s_add_u32 s18, s3, s16
	v_lshrrev_b32_e32 v2, 8, v7
	v_mov_b32_e32 v3, 0
	v_readlane_b32 s36, v254, 13
	s_addc_u32 s19, s33, s17
	s_bfe_u32 s20, s0, 0x40001
	s_lshr_b32 s1, s1, 4
	v_lshlrev_b64 v[4:5], 22, v[2:3]
	v_readlane_b32 s46, v254, 23
	v_readlane_b32 s47, v254, 24
	v_lshlrev_b32_e32 v2, 4, v7
	s_and_b64 s[16:17], vcc, exec
	v_readlane_b32 s23, v254, 7
	v_readlane_b32 s37, v254, 14
	v_readlane_b32 s40, v254, 17
	v_lshl_add_u64 v[4:5], s[46:47], 0, v[4:5]
	v_and_b32_e32 v2, 0xe00, v2
	s_cselect_b32 s16, s8, s18
	s_movk_i32 s18, 0x400
	s_cselect_b32 s36, s1, s20
	s_cselect_b32 s1, 15, 1
	v_readlane_b32 s22, v254, 6
	v_mov_b32_e32 v6, s23
	v_lshl_add_u64 v[2:3], v[4:5], 0, v[2:3]
	s_cselect_b32 s17, s9, s19
	s_cselect_b32 s37, s18, 0x440
	s_and_b32 s40, s0, s1
	v_readlane_b32 s21, v254, 5
	v_readlane_b32 s38, v254, 15
	v_readlane_b32 s39, v254, 16
	v_cndmask_b32_e32 v19, v3, v6, vcc
	v_mov_b32_e32 v3, s22
	s_and_b64 s[0:1], vcc, exec
	v_cndmask_b32_e32 v18, v2, v3, vcc
	s_mov_b32 s39, 0
	s_cselect_b32 s38, 0x400, 0
	s_mov_b64 s[18:19], 0x400
	s_mov_b64 s[20:21], 0
	v_readlane_b32 s41, v254, 18
	v_readlane_b32 s42, v254, 19
	v_readlane_b32 s43, v254, 20
	v_readlane_b32 s44, v254, 21
	v_readlane_b32 s45, v254, 22
	v_readlane_b32 s48, v254, 25
	v_readlane_b32 s49, v254, 26
	v_readlane_b32 s50, v254, 27
	v_readlane_b32 s51, v254, 28
	s_branch .Lq_14

.LBB0_520:
	s_setprio 0
	s_cmp_lt_i32 s8, 4
	s_cselect_b64 s[0:1], -1, 0
	s_cmp_gt_i32 s9, 3
	s_cselect_b64 s[2:3], -1, 0
	s_and_b64 s[0:1], s[0:1], s[2:3]
	s_andn2_b64 vcc, exec, s[0:1]
	s_cbranch_vccnz .LBB0_614
	v_readlane_b32 s0, v254, 10
	s_lshr_b32 s0, s0, 6
	s_sub_i32 s1, 0, s0
	v_cvt_f32_u32_e32 v0, s0
	v_and_b32_e32 v145, 63, v200
	v_rcp_iflag_f32_e32 v0, v0
	s_nop 0
	v_mul_f32_e32 v0, 0x4f7ffffe, v0
	v_cvt_u32_f32_e32 v1, v0
	v_bfe_u32 v0, v200, 6, 3
	v_cmp_eq_u32_e32 vcc, 0, v0
	v_readfirstlane_b32 s2, v1
	s_mul_i32 s1, s1, s2
	s_mul_hi_u32 s1, s2, s1
	s_add_i32 s2, s2, s1
	s_lshr_b32 s1, s2, 25
	s_mul_i32 s2, s1, s0
	s_sub_i32 s2, 0x80, s2
	s_add_i32 s3, s1, 1
	s_sub_i32 s4, s2, s0
	s_cmp_ge_u32 s2, s0
	s_cselect_b32 s1, s3, s1
	s_cselect_b32 s2, s4, s2
	s_add_i32 s3, s1, 1
	s_cmp_ge_u32 s2, s0
	s_cselect_b32 s2, s3, s1
	s_lshl_b32 s92, s2, 3
	v_cndmask_b32_e64 v1, 0, 8, vcc
	v_add_u32_e32 v182, s92, v1
	v_cmp_lt_u32_e64 s[0:1], v145, v182
	s_and_saveexec_b64 s[6:7], s[0:1]
	s_cbranch_execz .LBB0_604
	v_mul_u32_u24_e32 v183, s2, v0
	v_lshlrev_b32_e32 v0, 4, v144
	v_lshrrev_b32_e32 v1, 5, v144
	v_and_b32_e32 v8, 0x3c0, v0
	v_bitop3_b32 v9, v0, 48, v144 bitop3:0x48
	v_bfe_u32 v0, v144, 2, 2
	v_bitop3_b32 v1, v1, v0, 1 bitop3:0x6c
	v_lshlrev_b32_e32 v184, 4, v1
	v_and_b32_e32 v1, 15, v144
	v_lshrrev_b32_e32 v2, 7, v144
	v_bfe_u32 v3, v144, 6, 1
	v_mov_b32_e32 v143, 0
	v_lshlrev_b32_e32 v190, 2, v1
	v_cmp_eq_u32_e64 s[2:3], 0, v1
	v_lshlrev_b32_e32 v142, 4, v1
	v_lshlrev_b32_e32 v1, 3, v144
	v_lshlrev_b32_e32 v187, 6, v3
	v_lshlrev_b32_e32 v188, 5, v2
	v_lshlrev_b32_e32 v203, 12, v3
	v_lshlrev_b32_e32 v205, 11, v2
	v_and_b32_e32 v2, 56, v1
	v_mov_b32_e32 v3, v143
	v_lshl_add_u64 v[150:151], s[90:91], 0, v[2:3]
	v_cvt_f32_u32_e32 v2, s92
	s_add_u32 s8, s90, 0x1bf78200
	s_addc_u32 s9, s91, 0
	s_add_u32 s12, s90, 0xf0f0000
	v_rcp_iflag_f32_e32 v2, v2
	s_addc_u32 s13, s91, 0
	s_add_u32 s16, s90, 0x1b108000
	v_lshrrev_b32_e32 v6, 6, v144
	v_mul_f32_e32 v2, 0x4f7ffffe, v2
	v_readlane_b32 s36, v254, 13
	v_cvt_u32_f32_e32 v2, v2
	s_addc_u32 s17, s91, 0
	v_bfe_u32 v4, v144, 5, 1
	v_lshlrev_b32_e32 v7, 10, v6
	v_readlane_b32 s38, v254, 15
	v_and_b32_e32 v5, 31, v144
	v_bitop3_b32 v0, v4, v0, 2 bitop3:0x36
	v_add_u32_e32 v186, 0, v7
	s_movk_i32 s0, 0x1e00
	v_readlane_b32 s39, v254, 16
	s_add_u32 s18, s38, 0xf8000000
	v_lshlrev_b32_e32 v185, 4, v0
	v_lshlrev_b32_e32 v0, 2, v144
	v_mad_u32_u24 v1, v6, s0, v186
	s_addc_u32 s19, s39, -1
	v_mul_u32_u24_e32 v3, 0x110, v5
	v_lshlrev_b32_e32 v4, 4, v4
	s_sub_i32 s0, 0, s92
	v_bfe_u32 v189, v144, 4, 2
	v_and_b32_e32 v0, 60, v0
	v_add3_u32 v206, v1, v3, v4
	v_mul_lo_u32 v4, s0, v2
	v_or3_b32 v140, v8, v9, v7
	v_lshlrev_b32_e32 v204, 6, v5
	v_lshl_add_u64 v[148:149], s[88:89], 0, v[142:143]
	v_readlane_b32 s37, v254, 14
	v_readlane_b32 s40, v254, 17
	v_readlane_b32 s41, v254, 18
	v_readlane_b32 s42, v254, 19
	v_readlane_b32 s43, v254, 20
	v_readlane_b32 s44, v254, 21
	v_readlane_b32 s45, v254, 22
	v_readlane_b32 s46, v254, 23
	v_readlane_b32 s47, v254, 24
	v_readlane_b32 s48, v254, 25
	v_readlane_b32 s49, v254, 26
	v_readlane_b32 s50, v254, 27
	v_readlane_b32 s51, v254, 28
	v_add_u32_e32 v1, v1, v142
	v_mul_u32_u24_e32 v3, 0x110, v189
	v_mul_hi_u32 v4, v2, v4
	v_or3_b32 v152, v7, v8, v9
	v_lshlrev_b32_e32 v142, 2, v0
	v_mbcnt_lo_u32_b32 v0, -1, 0
	s_mov_b64 s[10:11], 0xf0f0000
	s_mov_b64 s[14:15], 0x1b108000
	v_or_b32_e32 v191, 4, v189
	v_or_b32_e32 v192, 8, v189
	v_or_b32_e32 v193, 12, v189
	v_or_b32_e32 v194, 16, v189
	v_or_b32_e32 v195, 20, v189
	v_or_b32_e32 v201, 24, v189
	v_or_b32_e32 v202, 28, v189
	v_mov_b32_e32 v141, v143
	v_add_u32_e32 v146, 0x1000, v140
	v_mov_b32_e32 v147, v143
	v_add3_u32 v207, 0, v203, v204
	v_add3_u32 v208, 0, v205, v204
	v_add_u32_e32 v209, v2, v4
	v_or_b32_e32 v154, 0x40000, v152
	v_mov_b32_e32 v155, v143
	v_or_b32_e32 v156, 0x808000, v152
	v_mov_b32_e32 v157, v143
	v_mov_b32_e32 v153, v143
	v_or_b32_e32 v158, 0x20000, v152
	v_mov_b32_e32 v159, v143
	v_or_b32_e32 v160, 0x404000, v152
	v_mov_b32_e32 v161, v143
	v_or_b32_e32 v162, 0x30000, v152
	v_mov_b32_e32 v163, v143
	v_add_u32_e32 v164, 0x606000, v152
	v_mov_b32_e32 v165, v143
	s_mov_b64 s[20:21], 0
	s_mov_b64 s[22:23], 0x202000
	s_mov_b64 s[24:25], 0x10000
	s_mov_b64 s[26:27], 0xf0f1000
	s_mov_b64 s[28:29], 0x1b109000
	s_mov_b64 s[30:31], 0x1b138000
	s_mov_b64 s[34:35], 0x1b139000
	s_mov_b64 s[36:37], 0x30000
	s_mov_b64 s[38:39], 0x606000
	s_mov_b64 s[40:41], 0x2000
	s_mov_b64 s[42:43], 0x3000
	s_mov_b64 s[44:45], 0x204000
	s_mov_b64 s[46:47], 0x205000
	s_mov_b64 s[48:49], 0xf4f4000
	s_mov_b64 s[50:51], 0xf4f5000
	s_mov_b64 s[56:57], 0xf4f6000
	s_mov_b64 s[58:59], 0xf4f7000
	s_mov_b64 s[60:61], 0x1b128000
	s_mov_b64 s[62:63], 0x1b129000
	s_mov_b64 s[64:65], 0xf0f2000
	s_mov_b64 s[66:67], 0xf0f3000
	s_mov_b64 s[68:69], 0x20000
	s_mov_b64 s[70:71], 0x404000
	s_mov_b32 s93, 0x8080
	v_mbcnt_hi_u32_b32 v210, -1, v0
	v_add_u32_e32 v211, v1, v3
	s_branch .LBB0_525
